# meta-row MFMA task in the in-proj phase: 8 operand loads issued together, progressive vmcnt instead of 4 serialized load-wait-mfma steps
# baseline (speedup 1.0000x reference)
.LBB0_778:
	v_lshl_add_u64 v[8:9], v[8:9], 0, v[148:149]
	v_lshl_add_u64 v[8:9], s[4:5], 1, v[8:9]
	global_load_dwordx4 v[14:17], v[0:1], off
	global_load_dwordx4 v[18:21], v[8:9], off
	global_load_dwordx4 v[184:187], v[0:1], off offset:64
	global_load_dwordx4 v[188:191], v[8:9], off offset:64
	global_load_dwordx4 v[192:195], v[0:1], off offset:128
	global_load_dwordx4 v[196:199], v[8:9], off offset:128
	global_load_dwordx4 v[200:203], v[0:1], off offset:192
	global_load_dwordx4 v[22:25], v[8:9], off offset:192
	s_andn2_b64 vcc, exec, s[8:9]
	s_waitcnt vmcnt(6)
	v_mfma_f32_16x16x32_bf16 v[14:17], v[18:21], v[14:17], 0
	s_waitcnt vmcnt(4)
	v_mfma_f32_16x16x32_bf16 v[14:17], v[188:191], v[184:187], v[14:17]
	s_waitcnt vmcnt(2)
	v_mfma_f32_16x16x32_bf16 v[14:17], v[196:199], v[192:195], v[14:17]
	s_waitcnt vmcnt(0)
	v_mfma_f32_16x16x32_bf16 v[14:17], v[22:25], v[200:203], v[14:17]
	s_nop 7
	ds_write_b128 v11, v[14:17]
	s_waitcnt lgkmcnt(0)
	s_barrier
	s_cbranch_vccnz .LBB0_773
	ds_read_b128 v[14:17], v10
	ds_read_b128 v[18:21], v10 offset:1024
	s_waitcnt lgkmcnt(0)
	v_pk_add_f32 v[8:9], v[16:17], v[20:21]
	v_pk_add_f32 v[18:19], v[14:15], v[18:19]
	ds_read_b128 v[14:17], v10 offset:2048
	s_waitcnt lgkmcnt(0)
	v_pk_add_f32 v[8:9], v[8:9], v[16:17]
	v_pk_add_f32 v[18:19], v[18:19], v[14:15]
	ds_read_b128 v[14:17], v10 offset:3072
	s_waitcnt lgkmcnt(0)
	v_pk_add_f32 v[8:9], v[8:9], v[16:17]
	v_pk_add_f32 v[18:19], v[18:19], v[14:15]
	ds_read_b128 v[14:17], v10 offset:4096
	s_waitcnt lgkmcnt(0)
	v_pk_add_f32 v[8:9], v[8:9], v[16:17]
	v_pk_add_f32 v[18:19], v[18:19], v[14:15]
	ds_read_b128 v[14:17], v10 offset:5120
	s_waitcnt lgkmcnt(0)
	v_pk_add_f32 v[8:9], v[8:9], v[16:17]
	v_pk_add_f32 v[18:19], v[18:19], v[14:15]
	ds_read_b128 v[14:17], v10 offset:6144
	s_waitcnt lgkmcnt(0)
	v_pk_add_f32 v[8:9], v[8:9], v[16:17]
	v_pk_add_f32 v[18:19], v[18:19], v[14:15]
	ds_read_b128 v[14:17], v10 offset:7168
	v_and_b32_e32 v26, 15, v210
	v_mul_u32_u24_e32 v26, 0xfc, v26
	v_add_u32_e32 v26, 0xe0000, v26
	v_mov_b32_e32 v27, 0
	v_lshl_add_u64 v[26:27], v[2:3], 0, v[26:27]
	global_load_dwordx4 v[64:67], v[26:27], off sc1
	global_load_dwordx4 v[68:71], v[26:27], off offset:16 sc1
	global_load_dwordx4 v[72:75], v[26:27], off offset:32 sc1
	global_load_dwordx4 v[76:79], v[26:27], off offset:48 sc1
	global_load_dwordx4 v[80:83], v[26:27], off offset:64 sc1
	global_load_dwordx4 v[84:87], v[26:27], off offset:80 sc1
	global_load_dwordx4 v[88:91], v[26:27], off offset:96 sc1
	global_load_dwordx4 v[92:95], v[26:27], off offset:112 sc1
	global_load_dwordx4 v[96:99], v[26:27], off offset:128 sc1
	global_load_dwordx4 v[100:103], v[26:27], off offset:144 sc1
	global_load_dwordx4 v[104:107], v[26:27], off offset:160 sc1
	global_load_dwordx4 v[108:111], v[26:27], off offset:176 sc1
	global_load_dwordx4 v[112:115], v[26:27], off offset:192 sc1
	global_load_dwordx4 v[116:119], v[26:27], off offset:208 sc1
	global_load_dwordx4 v[120:123], v[26:27], off offset:224 sc1
	global_load_dwordx4 v[124:127], v[26:27], off offset:240 sc1
	s_waitcnt lgkmcnt(0)
	v_pk_add_f32 v[14:15], v[18:19], v[14:15]
	v_pk_add_f32 v[8:9], v[8:9], v[16:17]
	s_waitcnt vmcnt(0)
	v_add_f32_e32 v64, v64, v65
	v_add_f32_e32 v66, v66, v67
	v_add_f32_e32 v64, v64, v66
	v_add_f32_e32 v68, v68, v69
	v_add_f32_e32 v70, v70, v71
	v_add_f32_e32 v68, v68, v70
	v_add_f32_e32 v72, v72, v73
	v_add_f32_e32 v74, v74, v75
	v_add_f32_e32 v72, v72, v74
	v_add_f32_e32 v76, v76, v77
	v_add_f32_e32 v78, v78, v79
	v_add_f32_e32 v76, v76, v78
	v_add_f32_e32 v80, v80, v81
	v_add_f32_e32 v82, v82, v83
	v_add_f32_e32 v80, v80, v82
	v_add_f32_e32 v84, v84, v85
	v_add_f32_e32 v86, v86, v87
	v_add_f32_e32 v84, v84, v86
	v_add_f32_e32 v88, v88, v89
	v_add_f32_e32 v90, v90, v91
	v_add_f32_e32 v88, v88, v90
	v_add_f32_e32 v92, v92, v93
	v_add_f32_e32 v94, v94, v95
	v_add_f32_e32 v92, v92, v94
	v_add_f32_e32 v96, v96, v97
	v_add_f32_e32 v98, v98, v99
	v_add_f32_e32 v96, v96, v98
	v_add_f32_e32 v100, v100, v101
	v_add_f32_e32 v102, v102, v103
	v_add_f32_e32 v100, v100, v102
	v_add_f32_e32 v104, v104, v105
	v_add_f32_e32 v106, v106, v107
	v_add_f32_e32 v104, v104, v106
	v_add_f32_e32 v108, v108, v109
	v_add_f32_e32 v110, v110, v111
	v_add_f32_e32 v108, v108, v110
	v_add_f32_e32 v112, v112, v113
	v_add_f32_e32 v114, v114, v115
	v_add_f32_e32 v112, v112, v114
	v_add_f32_e32 v116, v116, v117
	v_add_f32_e32 v118, v118, v119
	v_add_f32_e32 v116, v116, v118
	v_add_f32_e32 v120, v120, v121
	v_add_f32_e32 v122, v122, v123
	v_add_f32_e32 v120, v120, v122
	v_add_f32_e32 v124, v124, v125
	v_add_f32_e32 v126, v126, v127
	v_add_f32_e32 v124, v124, v126
	v_add_f32_e32 v64, v64, v68
	v_add_f32_e32 v72, v72, v76
	v_add_f32_e32 v80, v80, v84
	v_add_f32_e32 v88, v88, v92
	v_add_f32_e32 v96, v96, v100
	v_add_f32_e32 v104, v104, v108
	v_add_f32_e32 v112, v112, v116
	v_add_f32_e32 v120, v120, v124
	v_add_f32_e32 v64, v64, v72
	v_add_f32_e32 v80, v80, v88
	v_add_f32_e32 v96, v96, v104
	v_add_f32_e32 v112, v112, v120
	v_add_f32_e32 v64, v64, v80
	v_add_f32_e32 v96, v96, v112
	v_add_f32_e32 v64, v64, v96
	v_mov_b32_e32 v7, v64
	v_fmamk_f32 v7, v7, 0x3a800000, v207
	v_rsq_f32_e32 v18, v7
	s_nop 0
	v_pk_mul_f32 v[16:17], v[8:9], v[18:19] op_sel_hi:[1,0]
	v_lshl_add_u64 v[8:9], v[4:5], 0, s[48:49]
	v_pk_mul_f32 v[14:15], v[14:15], v[18:19] op_sel_hi:[1,0]
	v_lshl_add_u64 v[18:19], v[8:9], 2, s[12:13]
	global_store_dwordx4 v[18:19], v[14:17], off
	v_lshl_add_u64 v[8:9], v[8:9], 1, s[2:3]
	s_nop 0
	v_cvt_pk_bf16_f32 v14, v14, v15
	v_cvt_pk_bf16_f32 v15, v16, v17
	global_store_dwordx2 v[8:9], v[14:15], off
	s_branch .LBB0_773
